# P4: sample tasks paced with s_sleep 80 per task so the scan (long pole) gets HBM bandwidth earlier
# baseline (speedup 1.0000x reference)
; __device__ __forceinline__ void sample_task(LAS unsigned char* lds, const SampP& P, int task, int tid, int lane, int wave) {
;     ...
;     const float* s0 = P.s0 + (size_t)(bs * 8 + h) * 16384; float* so = P.oss + (size_t)(bs * 8 + h) * 16384;
;     const int half = lane >> 5, c4 = (lane & 31) * 4;
;     f32x4 sr[8];
; #pragma unroll
;     for (int i = 0; i < 8; ++i) sr[i] = *(const f32x4*)(s0 + (size_t)(wave * 16 + 2 * i + half) * 128 + c4);
;     const float* zr = P.zs + (size_t)bs * DINP;
;     const float zbeta = zr[8192 + h], zalpha = zr[8200 + h], alg = P.alog[h], dtbv = P.dtb[h];
;     f32x4 ongv = {0.f, 0.f, 0.f, 0.f}, gbv = {0.f, 0.f, 0.f, 0.f};
;     if (wave == 0 && lane < 32) { ongv = *(const f32x4*)(P.ong + c4); gbv = *(const f32x4*)(zr + 7168 + h * 128 + c4); }
; __global__ void __launch_bounds__(512, 2) mega(Args a) {
;     ...
;             for (int task = bx - 2 * NB * NH; task < DECB * NH; task += G - 2 * NB * NH) sample_task(lds, P, task, tid, lane, wave);
.LBB0_479:
	s_sleep 80
	v_lshl_add_u64 v[4:5], v[104:105], 0, v[102:103]
	global_load_dwordx4 v[40:43], v[4:5], off
	v_lshl_add_u64 v[4:5], v[106:107], 0, v[102:103]
	global_load_dwordx4 v[36:39], v[4:5], off
	v_lshl_add_u64 v[4:5], v[108:109], 0, v[102:103]
	global_load_dwordx4 v[32:35], v[4:5], off
	v_lshl_add_u64 v[4:5], v[110:111], 0, v[102:103]
	global_load_dwordx4 v[28:31], v[4:5], off
	v_lshl_add_u64 v[4:5], v[112:113], 0, v[102:103]
	global_load_dwordx4 v[24:27], v[4:5], off
	v_lshl_add_u64 v[4:5], v[114:115], 0, v[102:103]
	global_load_dwordx4 v[20:23], v[4:5], off
	v_lshl_add_u64 v[4:5], v[116:117], 0, v[102:103]
	s_addk_i32 s34, 0xc0
	global_load_dwordx4 v[16:19], v[4:5], off
	v_lshl_add_u64 v[4:5], v[118:119], 0, v[102:103]
	global_load_dwordx4 v[12:15], v[4:5], off
	s_ashr_i32 s26, s34, 3
	v_mov_b32_e32 v4, 0x8080
	v_mad_i64_i32 v[138:139], s[10:11], s26, v4, v[46:47]
	v_lshl_add_u64 v[4:5], v[138:139], 0, s[38:39]
	v_add_co_u32_e32 v4, vcc, 0x8000, v4
	v_mov_b32_e32 v136, 0
	s_nop 0
	v_addc_co_u32_e32 v5, vcc, 0, v5, vcc
	global_load_dword v163, v[4:5], off
	global_load_dword v160, v[4:5], off offset:32
	global_load_dword v162, v[58:59], off
	global_load_dword v161, v[60:61], off
	v_mov_b32_e32 v8, 0
	v_mov_b32_e32 v9, 0
	v_mov_b32_e32 v10, 0
	v_mov_b32_e32 v11, 0
	v_mov_b32_e32 v4, 0
	v_mov_b32_e32 v5, 0
	v_mov_b32_e32 v6, 0
	v_mov_b32_e32 v7, 0
	s_and_saveexec_b64 s[10:11], s[22:23]
	s_cbranch_execz .LBB0_481
	s_mov_b32 s25, s39
	v_lshl_add_u64 v[4:5], v[138:139], 0, s[24:25]
	v_lshl_add_u64 v[8:9], v[4:5], 0, v[152:153]
	v_add_co_u32_e32 v8, vcc, 0x7000, v8
	global_load_dwordx4 v[4:7], v[56:57], off
	s_nop 0
	v_addc_co_u32_e32 v9, vcc, 0, v9, vcc
	global_load_dwordx4 v[8:11], v[8:9], off
